# NSA tile loops: scalar mask tests instead of VALU ballot idioms
# baseline (speedup 1.0000x reference)
; #define LAS __attribute__((address_space(3)))
; #define MFMA32(a, b, c) __builtin_amdgcn_mfma_f32_32x32x16_bf16((a), (b), (c), 0, 0, 0)
; template <int MODE>
; DI void nsa_tile(LAS const unsigned char* buf, const bf16x8 (&qf)[4], f32x16 (&o)[2], float& m, float& l, int kbase0, int t, bool lanesel, float slope2, int c, int hi) {
;     ...
;     for (int sub = 0; sub < 2; ++sub) {
;         const int klo = kbase0 + 32 * sub;
;         bool full, none;
;         if (MODE == 0) { full = lanesel && (klo + 31 <= t); none = !lanesel || (klo > t); }
;         else { full = (klo + 31 <= t) && (klo >= t - 511); none = (klo > t) || (klo + 31 < t - 511); }
;         if (__all(none)) continue;
;         int dbase = t - klo - 4 * hi;
;         asm volatile("" : "+v"(dbase));
;         const float b0 = none ? -1e30f : -slope2 * (float)dbase;
;         f32x16 s;
; #pragma unroll
;         for (int i = 0; i < 16; ++i) s[i] = fmaf(slope2, (float)((i & 3) + 8 * (i >> 2)), b0);
; #pragma unroll
;         for (int st = 0; st < 4; ++st) {
;             const bf16x8 a = *(LAS const bf16x8*)(buf + (32 * sub + c) * 144 + st * 32 + hi * 16);
;             s = MFMA32(a, qf[st], s);
;         }
;         if (__any(!full && !none)) {
; #pragma unroll
;             for (int i = 0; i < 16; ++i) {
;                 const int dist = dbase - ((i & 3) + 8 * (i >> 2));
;                 const bool valid = (MODE == 0) ? (lanesel && dist >= 0) : ((unsigned)dist < 512u);
;                 if (!valid) s[i] = -1e30f;
;             }
;         }
; DI void nsa_unit(const Params& p, LAS unsigned char* lds, unsigned char* ldsg, int bg, int qt, int tid) {
;     ...
;             const int nb = LIST[i];
;             if (i + 2 < nl) { const int nb2 = LIST[i + 2]; rk2 = *(const u32x4*)(Ksrc + (size_t)(64 * nb2) * NPROJ); rv2 = *(const u32x4*)(Vsrc + 64 * nb2); }
;             const bool lanesel = (SEL[(4 * w + qi) * 4 + (nb >> 5)] >> (nb & 31)) & 1u;
;             if (__any(lanesel))
;                 nsa_tile<0>(lds + cb * NSA_TBUF, qf, o, m, l, 64 * nb, t, lanesel, slope2, c, hi);
.LBB0_822:
	s_ashr_i32 s2, s4, 5
	v_lshl_add_u32 v80, s2, 2, v113
	ds_read_b32 v80, v80
	s_and_b32 s2, s4, 31
	s_waitcnt lgkmcnt(0)
	v_lshrrev_b32_e32 v81, s4, v80
	v_bfe_u32 v80, v80, s2, 1
	v_and_b32_e32 v81, 1, v81
	v_cmp_ne_u32_e32 vcc, 0, v80
	v_cmp_eq_u32_e64 s[2:3], 1, v81
	s_cbranch_vccz .LBB0_835
	s_lshl_b32 s15, s4, 6
	s_xor_b64 s[6:7], s[2:3], -1
	v_cmp_gt_i32_e32 vcc, s15, v150
	s_mul_i32 s5, s11, 0x4600
	s_or_b64 vcc, vcc, s[6:7]
	s_add_i32 s14, s5, 0
	v_add_u32_e32 v80, s14, v0
	s_mov_b64 s[4:5], vcc
	s_cmp_eq_u64 s[4:5], exec
	v_add_u32_e32 v119, v80, v171
	s_cbranch_scc1 .LBB0_829
	v_subrev_u32_e32 v120, s15, v117
	ds_read_b128 v[122:125], v119
	v_cvt_f32_i32_e32 v80, v120
	s_or_b32 s4, s15, 31
	v_cmp_gt_i32_e64 s[4:5], s4, v150
	s_or_b64 s[4:5], s[6:7], s[4:5]
	v_mul_f32_e64 v80, -v152, v80
	v_cndmask_b32_e32 v94, v80, v164, vcc
	v_sub_f32_e32 v94, v94, v248
	v_fma_f32 v80, 0, v152, v94
	v_add_f32_e32 v81, v152, v94
	v_pk_fma_f32 v[82:83], v[152:153], s[72:73], v[94:95] op_sel_hi:[1,1,0]
	v_pk_fma_f32 v[84:85], v[152:153], s[74:75], v[94:95] op_sel_hi:[1,1,0]
	v_pk_fma_f32 v[86:87], v[152:153], s[76:77], v[94:95] op_sel_hi:[1,1,0]
	v_pk_fma_f32 v[88:89], v[152:153], s[70:71], v[94:95] op_sel_hi:[1,1,0]
	v_pk_fma_f32 v[90:91], v[152:153], s[78:79], v[94:95] op_sel_hi:[1,1,0]
	v_pk_fma_f32 v[92:93], v[152:153], s[80:81], v[94:95] op_sel_hi:[1,1,0]
	v_pk_fma_f32 v[94:95], v[152:153], s[82:83], v[94:95] op_sel_hi:[1,1,0]
	s_xor_b64 s[4:5], vcc, s[4:5]
	s_waitcnt lgkmcnt(0)
	v_mfma_f32_32x32x16_bf16 v[80:95], v[122:125], v[128:131], v[80:95]
	ds_read_b128 v[122:125], v119 offset:32
	s_waitcnt lgkmcnt(0)
	v_mfma_f32_32x32x16_bf16 v[80:95], v[122:125], v[132:135], v[80:95]
	ds_read_b128 v[122:125], v119 offset:64
	s_waitcnt lgkmcnt(0)
	v_mfma_f32_32x32x16_bf16 v[80:95], v[122:125], v[136:139], v[80:95]
	ds_read_b128 v[122:125], v119 offset:96
	s_waitcnt lgkmcnt(0)
	v_mfma_f32_32x32x16_bf16 v[80:95], v[122:125], v[140:143], v[80:95]
	s_cmp_lg_u64 s[4:5], 0
	s_cbranch_scc0 .LBB0_826
	v_cmp_lt_i32_e32 vcc, -1, v120
	s_and_b64 vcc, s[2:3], vcc
	s_nop 8
	v_cndmask_b32_e32 v80, v164, v80, vcc
	v_cmp_lt_i32_e32 vcc, 0, v120
	s_and_b64 vcc, s[2:3], vcc
	s_nop 0
	v_cndmask_b32_e32 v81, v164, v81, vcc
	v_cmp_lt_i32_e32 vcc, 1, v120
	s_and_b64 vcc, s[2:3], vcc
	s_nop 0
	v_cndmask_b32_e32 v82, v164, v82, vcc
	v_cmp_lt_i32_e32 vcc, 2, v120
	s_and_b64 vcc, s[2:3], vcc
	s_nop 0
	v_cndmask_b32_e32 v83, v164, v83, vcc
	v_cmp_lt_i32_e32 vcc, 7, v120
	s_and_b64 vcc, s[2:3], vcc
	s_nop 0
	v_cndmask_b32_e32 v84, v164, v84, vcc
	v_cmp_lt_i32_e32 vcc, 8, v120
	s_and_b64 vcc, s[2:3], vcc
	s_nop 0
	v_cndmask_b32_e32 v85, v164, v85, vcc
	v_cmp_lt_i32_e32 vcc, 9, v120
	s_and_b64 vcc, s[2:3], vcc
	s_nop 0
	v_cndmask_b32_e32 v86, v164, v86, vcc
	v_cmp_lt_i32_e32 vcc, 10, v120
	s_and_b64 vcc, s[2:3], vcc
	s_nop 0
	v_cndmask_b32_e32 v87, v164, v87, vcc
	v_cmp_lt_i32_e32 vcc, 15, v120
	s_and_b64 vcc, s[2:3], vcc
	s_nop 0
	v_cndmask_b32_e32 v88, v164, v88, vcc
	v_cmp_lt_i32_e32 vcc, 16, v120
	s_and_b64 vcc, s[2:3], vcc
	s_nop 0
	v_cndmask_b32_e32 v89, v164, v89, vcc
	v_cmp_lt_i32_e32 vcc, 17, v120
	s_and_b64 vcc, s[2:3], vcc
	s_nop 0
	v_cndmask_b32_e32 v90, v164, v90, vcc
	v_cmp_lt_i32_e32 vcc, 18, v120
	s_and_b64 vcc, s[2:3], vcc
	s_nop 0
	v_cndmask_b32_e32 v91, v164, v91, vcc
	v_cmp_lt_i32_e32 vcc, 23, v120
	s_and_b64 vcc, s[2:3], vcc
	s_nop 0
	v_cndmask_b32_e32 v92, v164, v92, vcc
	v_cmp_lt_i32_e32 vcc, 24, v120
	s_and_b64 vcc, s[2:3], vcc
	s_nop 0
	v_cndmask_b32_e32 v93, v164, v93, vcc
	v_cmp_lt_i32_e32 vcc, 25, v120
	s_and_b64 vcc, s[2:3], vcc
	s_nop 0
	v_cndmask_b32_e32 v94, v164, v94, vcc
	v_cmp_lt_i32_e32 vcc, 26, v120
	s_and_b64 vcc, s[2:3], vcc
	s_nop 0
	v_cndmask_b32_e32 v95, v164, v95, vcc

; #define LAS __attribute__((address_space(3)))
; #define MFMA32(a, b, c) __builtin_amdgcn_mfma_f32_32x32x16_bf16((a), (b), (c), 0, 0, 0)
; template <int MODE>
; DI void nsa_tile(LAS const unsigned char* buf, const bf16x8 (&qf)[4], f32x16 (&o)[2], float& m, float& l, int kbase0, int t, bool lanesel, float slope2, int c, int hi) {
;     ...
;     for (int sub = 0; sub < 2; ++sub) {
;         const int klo = kbase0 + 32 * sub;
;         bool full, none;
;         if (MODE == 0) { full = lanesel && (klo + 31 <= t); none = !lanesel || (klo > t); }
;         else { full = (klo + 31 <= t) && (klo >= t - 511); none = (klo > t) || (klo + 31 < t - 511); }
;         if (__all(none)) continue;
;         int dbase = t - klo - 4 * hi;
;         asm volatile("" : "+v"(dbase));
;         const float b0 = none ? -1e30f : -slope2 * (float)dbase;
;         f32x16 s;
; #pragma unroll
;         for (int i = 0; i < 16; ++i) s[i] = fmaf(slope2, (float)((i & 3) + 8 * (i >> 2)), b0);
; #pragma unroll
;         for (int st = 0; st < 4; ++st) {
;             const bf16x8 a = *(LAS const bf16x8*)(buf + (32 * sub + c) * 144 + st * 32 + hi * 16);
;             s = MFMA32(a, qf[st], s);
;         }
;         if (__any(!full && !none)) {
; #pragma unroll
;             for (int i = 0; i < 16; ++i) {
;                 const int dist = dbase - ((i & 3) + 8 * (i >> 2));
;                 const bool valid = (MODE == 0) ? (lanesel && dist >= 0) : ((unsigned)dist < 512u);
;                 if (!valid) s[i] = -1e30f;
;             }
;         }
.LBB0_829:
	s_or_b32 s16, s15, 32
	v_cmp_gt_i32_e32 vcc, s16, v150
	s_or_b64 vcc, s[6:7], vcc
	s_nop 0
	s_mov_b64 s[4:5], vcc
	s_cmp_eq_u64 s[4:5], exec
	s_cbranch_scc1 .LBB0_835
	v_subrev_u32_e32 v120, s16, v117
	ds_read_b128 v[122:125], v119 offset:4608
	v_cvt_f32_i32_e32 v80, v120
	s_or_b32 s4, s15, 63
	v_cmp_gt_i32_e64 s[4:5], s4, v150
	s_xor_b64 s[6:7], vcc, -1
	v_mul_f32_e64 v80, -v152, v80
	v_cndmask_b32_e32 v94, v80, v164, vcc
	v_sub_f32_e32 v94, v94, v248
	v_fma_f32 v80, 0, v152, v94
	v_add_f32_e32 v81, v152, v94
	v_pk_fma_f32 v[82:83], v[152:153], s[72:73], v[94:95] op_sel_hi:[1,1,0]
	v_pk_fma_f32 v[84:85], v[152:153], s[74:75], v[94:95] op_sel_hi:[1,1,0]
	v_pk_fma_f32 v[86:87], v[152:153], s[76:77], v[94:95] op_sel_hi:[1,1,0]
	v_pk_fma_f32 v[88:89], v[152:153], s[70:71], v[94:95] op_sel_hi:[1,1,0]
	v_pk_fma_f32 v[90:91], v[152:153], s[78:79], v[94:95] op_sel_hi:[1,1,0]
	v_pk_fma_f32 v[92:93], v[152:153], s[80:81], v[94:95] op_sel_hi:[1,1,0]
	v_pk_fma_f32 v[94:95], v[152:153], s[82:83], v[94:95] op_sel_hi:[1,1,0]
	s_and_b64 s[4:5], s[6:7], s[4:5]
	s_waitcnt lgkmcnt(0)
	v_mfma_f32_32x32x16_bf16 v[80:95], v[122:125], v[128:131], v[80:95]
	ds_read_b128 v[122:125], v119 offset:4640
	s_waitcnt lgkmcnt(0)
	v_mfma_f32_32x32x16_bf16 v[80:95], v[122:125], v[132:135], v[80:95]
	ds_read_b128 v[122:125], v119 offset:4672
	s_waitcnt lgkmcnt(0)
	v_mfma_f32_32x32x16_bf16 v[80:95], v[122:125], v[136:139], v[80:95]
	ds_read_b128 v[122:125], v119 offset:4704
	s_waitcnt lgkmcnt(0)
	v_mfma_f32_32x32x16_bf16 v[80:95], v[122:125], v[140:143], v[80:95]
	s_cmp_lg_u64 s[4:5], 0
	s_cbranch_scc0 .LBB0_832
	v_cmp_lt_i32_e32 vcc, -1, v120
	s_and_b64 vcc, s[2:3], vcc
	s_nop 8
	v_cndmask_b32_e32 v80, v164, v80, vcc
	v_cmp_lt_i32_e32 vcc, 0, v120
	s_and_b64 vcc, s[2:3], vcc
	s_nop 0
	v_cndmask_b32_e32 v81, v164, v81, vcc
	v_cmp_lt_i32_e32 vcc, 1, v120
	s_and_b64 vcc, s[2:3], vcc
	s_nop 0
	v_cndmask_b32_e32 v82, v164, v82, vcc
	v_cmp_lt_i32_e32 vcc, 2, v120
	s_and_b64 vcc, s[2:3], vcc
	s_nop 0
	v_cndmask_b32_e32 v83, v164, v83, vcc
	v_cmp_lt_i32_e32 vcc, 7, v120
	s_and_b64 vcc, s[2:3], vcc
	s_nop 0
	v_cndmask_b32_e32 v84, v164, v84, vcc
	v_cmp_lt_i32_e32 vcc, 8, v120
	s_and_b64 vcc, s[2:3], vcc
	s_nop 0
	v_cndmask_b32_e32 v85, v164, v85, vcc
	v_cmp_lt_i32_e32 vcc, 9, v120
	s_and_b64 vcc, s[2:3], vcc
	s_nop 0
	v_cndmask_b32_e32 v86, v164, v86, vcc
	v_cmp_lt_i32_e32 vcc, 10, v120
	s_and_b64 vcc, s[2:3], vcc
	s_nop 0
	v_cndmask_b32_e32 v87, v164, v87, vcc
	v_cmp_lt_i32_e32 vcc, 15, v120
	s_and_b64 vcc, s[2:3], vcc
	s_nop 0
	v_cndmask_b32_e32 v88, v164, v88, vcc
	v_cmp_lt_i32_e32 vcc, 16, v120
	s_and_b64 vcc, s[2:3], vcc
	s_nop 0
	v_cndmask_b32_e32 v89, v164, v89, vcc
	v_cmp_lt_i32_e32 vcc, 17, v120
	s_and_b64 vcc, s[2:3], vcc
	s_nop 0
	v_cndmask_b32_e32 v90, v164, v90, vcc
	v_cmp_lt_i32_e32 vcc, 18, v120
	s_and_b64 vcc, s[2:3], vcc
	s_nop 0
	v_cndmask_b32_e32 v91, v164, v91, vcc
	v_cmp_lt_i32_e32 vcc, 23, v120
	s_and_b64 vcc, s[2:3], vcc
	s_nop 0
	v_cndmask_b32_e32 v92, v164, v92, vcc
	v_cmp_lt_i32_e32 vcc, 24, v120
	s_and_b64 vcc, s[2:3], vcc
	s_nop 0
	v_cndmask_b32_e32 v93, v164, v93, vcc
	v_cmp_lt_i32_e32 vcc, 25, v120
	s_and_b64 vcc, s[2:3], vcc
	s_nop 0
	v_cndmask_b32_e32 v94, v164, v94, vcc
	v_cmp_lt_i32_e32 vcc, 26, v120
	s_and_b64 vcc, s[2:3], vcc
	s_nop 0
	v_cndmask_b32_e32 v95, v164, v95, vcc

; #define LAS __attribute__((address_space(3)))
; #define MFMA32(a, b, c) __builtin_amdgcn_mfma_f32_32x32x16_bf16((a), (b), (c), 0, 0, 0)
; template <int MODE>
; DI void nsa_tile(LAS const unsigned char* buf, const bf16x8 (&qf)[4], f32x16 (&o)[2], float& m, float& l, int kbase0, int t, bool lanesel, float slope2, int c, int hi) {
;     ...
;     for (int sub = 0; sub < 2; ++sub) {
;         const int klo = kbase0 + 32 * sub;
;         bool full, none;
;         if (MODE == 0) { full = lanesel && (klo + 31 <= t); none = !lanesel || (klo > t); }
;         else { full = (klo + 31 <= t) && (klo >= t - 511); none = (klo > t) || (klo + 31 < t - 511); }
;         if (__all(none)) continue;
;         int dbase = t - klo - 4 * hi;
;         asm volatile("" : "+v"(dbase));
;         const float b0 = none ? -1e30f : -slope2 * (float)dbase;
;         f32x16 s;
; #pragma unroll
;         for (int i = 0; i < 16; ++i) s[i] = fmaf(slope2, (float)((i & 3) + 8 * (i >> 2)), b0);
; #pragma unroll
;         for (int st = 0; st < 4; ++st) {
;             const bf16x8 a = *(LAS const bf16x8*)(buf + (32 * sub + c) * 144 + st * 32 + hi * 16);
;             s = MFMA32(a, qf[st], s);
;         }
;         if (__any(!full && !none)) {
; #pragma unroll
;             for (int i = 0; i < 16; ++i) {
;                 const int dist = dbase - ((i & 3) + 8 * (i >> 2));
;                 const bool valid = (MODE == 0) ? (lanesel && dist >= 0) : ((unsigned)dist < 512u);
;                 if (!valid) s[i] = -1e30f;
;             }
;         }
; DI void nsa_unit(const Params& p, LAS unsigned char* lds, unsigned char* ldsg, int bg, int qt, int tid) {
;     ...
;         for (int kt = kt_lo; kt <= kt_hi; ++kt) {
;             if (kt + 2 <= kt_hi) { rk2 = *(const u32x4*)(Ksrc + (size_t)(64 * (kt + 2)) * NPROJ); rv2 = *(const u32x4*)(Vsrc + 64 * (kt + 2)); }
;             if (!(64 * kt + 63 < tw0 - 511 || 64 * kt > tw0 + 3))
;                 nsa_tile<1>(lds + cb * NSA_TBUF, qf, o, m, l, 64 * kt, t, true, slope2, c, hi);
.LBB0_846:
	s_add_i32 s11, s8, 63
	s_cmp_lt_i32 s11, s40
	s_cselect_b64 s[2:3], -1, 0
	s_cmp_gt_i32 s8, s55
	s_cselect_b64 s[4:5], -1, 0
	s_or_b64 s[2:3], s[4:5], s[2:3]
	s_and_b64 vcc, exec, s[2:3]
	s_cbranch_vccnz .LBB0_859
	s_mul_i32 s2, s9, 0x4600
	s_add_i32 s4, s8, 31
	s_add_i32 s10, s2, 0
	v_cmp_gt_i32_e32 vcc, s8, v150
	v_cmp_lt_i32_e64 s[2:3], s4, v178
	s_or_b64 vcc, vcc, s[2:3]
	v_add_u32_e32 v112, s10, v0
	s_mov_b64 s[2:3], vcc
	s_cmp_eq_u64 s[2:3], exec
	v_add_u32_e32 v181, v112, v171
	s_cbranch_scc1 .LBB0_853
	v_add_u32_e32 v182, 32, v179
	ds_read_b128 v[184:187], v181
	v_cvt_f32_i32_e32 v112, v182
	v_cmp_gt_i32_e64 s[2:3], s4, v150
	v_cmp_lt_i32_e64 s[4:5], s8, v178
	s_or_b64 s[2:3], s[2:3], s[4:5]
	v_mul_f32_e64 v112, -v152, v112
	v_cndmask_b32_e32 v126, v112, v164, vcc
	v_sub_f32_e32 v126, v126, v249
	v_fma_f32 v112, 0, v152, v126
	v_add_f32_e32 v113, v152, v126
	v_pk_fma_f32 v[114:115], v[152:153], s[72:73], v[126:127] op_sel_hi:[1,1,0]
	v_pk_fma_f32 v[116:117], v[152:153], s[74:75], v[126:127] op_sel_hi:[1,1,0]
	v_pk_fma_f32 v[118:119], v[152:153], s[76:77], v[126:127] op_sel_hi:[1,1,0]
	v_pk_fma_f32 v[120:121], v[152:153], s[70:71], v[126:127] op_sel_hi:[1,1,0]
	v_pk_fma_f32 v[122:123], v[152:153], s[78:79], v[126:127] op_sel_hi:[1,1,0]
	v_pk_fma_f32 v[124:125], v[152:153], s[80:81], v[126:127] op_sel_hi:[1,1,0]
	v_pk_fma_f32 v[126:127], v[152:153], s[82:83], v[126:127] op_sel_hi:[1,1,0]
	s_xor_b64 s[4:5], vcc, -1
	s_and_b64 s[2:3], s[2:3], s[4:5]
	s_waitcnt lgkmcnt(0)
	v_mfma_f32_32x32x16_bf16 v[112:127], v[184:187], v[128:131], v[112:127]
	ds_read_b128 v[184:187], v181 offset:32
	s_waitcnt lgkmcnt(0)
	v_mfma_f32_32x32x16_bf16 v[112:127], v[184:187], v[132:135], v[112:127]
	ds_read_b128 v[184:187], v181 offset:64
	s_waitcnt lgkmcnt(0)
	v_mfma_f32_32x32x16_bf16 v[112:127], v[184:187], v[136:139], v[112:127]
	ds_read_b128 v[184:187], v181 offset:96
	s_waitcnt lgkmcnt(0)
	v_mfma_f32_32x32x16_bf16 v[112:127], v[184:187], v[140:143], v[112:127]
	s_cmp_lg_u64 s[2:3], 0
	s_cbranch_scc0 .LBB0_850
	v_cmp_gt_u32_e32 vcc, s89, v182
	v_add_u32_e32 v183, -1, v182
	s_nop 8
	v_cndmask_b32_e32 v112, v164, v112, vcc
	v_cmp_gt_u32_e32 vcc, s89, v183
	v_add_u32_e32 v183, -2, v182
	s_nop 0
	v_cndmask_b32_e32 v113, v164, v113, vcc
	v_cmp_gt_u32_e32 vcc, s89, v183
	v_add_u32_e32 v183, -3, v182
	s_nop 0
	v_cndmask_b32_e32 v114, v164, v114, vcc
	v_cmp_gt_u32_e32 vcc, s89, v183
	v_add_u32_e32 v183, -8, v182
	s_nop 0
	v_cndmask_b32_e32 v115, v164, v115, vcc
	v_cmp_gt_u32_e32 vcc, s89, v183
	v_add_u32_e32 v183, -9, v182
	s_nop 0
	v_cndmask_b32_e32 v116, v164, v116, vcc
	v_cmp_gt_u32_e32 vcc, s89, v183
	v_add_u32_e32 v183, -10, v182
	s_nop 0
	v_cndmask_b32_e32 v117, v164, v117, vcc
	v_cmp_gt_u32_e32 vcc, s89, v183
	v_add_u32_e32 v183, -11, v182
	s_nop 0
	v_cndmask_b32_e32 v118, v164, v118, vcc
	v_cmp_gt_u32_e32 vcc, s89, v183
	v_add_u32_e32 v183, -16, v182
	s_nop 0
	v_cndmask_b32_e32 v119, v164, v119, vcc
	v_cmp_gt_u32_e32 vcc, s89, v183
	v_subrev_u32_e32 v183, 17, v182
	s_nop 0
	v_cndmask_b32_e32 v120, v164, v120, vcc
	v_cmp_gt_u32_e32 vcc, s89, v183
	v_subrev_u32_e32 v183, 18, v182
	s_nop 0
	v_cndmask_b32_e32 v121, v164, v121, vcc
	v_cmp_gt_u32_e32 vcc, s89, v183
	v_subrev_u32_e32 v183, 19, v182
	s_nop 0
	v_cndmask_b32_e32 v122, v164, v122, vcc
	v_cmp_gt_u32_e32 vcc, s89, v183
	v_subrev_u32_e32 v183, 24, v182
	s_nop 0
	v_cndmask_b32_e32 v123, v164, v123, vcc
	v_cmp_gt_u32_e32 vcc, s89, v183
	v_subrev_u32_e32 v183, 25, v182
	s_nop 0
	v_cndmask_b32_e32 v124, v164, v124, vcc
	v_cmp_gt_u32_e32 vcc, s89, v183
	v_subrev_u32_e32 v183, 26, v182
	v_subrev_u32_e32 v182, 27, v182
	v_cndmask_b32_e32 v125, v164, v125, vcc
	v_cmp_gt_u32_e32 vcc, s89, v183
	s_nop 1
	v_cndmask_b32_e32 v126, v164, v126, vcc
	v_cmp_gt_u32_e32 vcc, s89, v182
	s_nop 1
	v_cndmask_b32_e32 v127, v164, v127, vcc

; #define LAS __attribute__((address_space(3)))
; #define MFMA32(a, b, c) __builtin_amdgcn_mfma_f32_32x32x16_bf16((a), (b), (c), 0, 0, 0)
; template <int MODE>
; DI void nsa_tile(LAS const unsigned char* buf, const bf16x8 (&qf)[4], f32x16 (&o)[2], float& m, float& l, int kbase0, int t, bool lanesel, float slope2, int c, int hi) {
;     ...
;     for (int sub = 0; sub < 2; ++sub) {
;         const int klo = kbase0 + 32 * sub;
;         bool full, none;
;         if (MODE == 0) { full = lanesel && (klo + 31 <= t); none = !lanesel || (klo > t); }
;         else { full = (klo + 31 <= t) && (klo >= t - 511); none = (klo > t) || (klo + 31 < t - 511); }
;         if (__all(none)) continue;
;         int dbase = t - klo - 4 * hi;
;         asm volatile("" : "+v"(dbase));
;         const float b0 = none ? -1e30f : -slope2 * (float)dbase;
;         f32x16 s;
; #pragma unroll
;         for (int i = 0; i < 16; ++i) s[i] = fmaf(slope2, (float)((i & 3) + 8 * (i >> 2)), b0);
; #pragma unroll
;         for (int st = 0; st < 4; ++st) {
;             const bf16x8 a = *(LAS const bf16x8*)(buf + (32 * sub + c) * 144 + st * 32 + hi * 16);
;             s = MFMA32(a, qf[st], s);
;         }
;         if (__any(!full && !none)) {
; #pragma unroll
;             for (int i = 0; i < 16; ++i) {
;                 const int dist = dbase - ((i & 3) + 8 * (i >> 2));
;                 const bool valid = (MODE == 0) ? (lanesel && dist >= 0) : ((unsigned)dist < 512u);
;                 if (!valid) s[i] = -1e30f;
;             }
;         }
.LBB0_853:
	s_add_i32 s4, s8, 32
	v_cmp_gt_i32_e32 vcc, s4, v150
	v_cmp_lt_i32_e64 s[2:3], s11, v178
	s_or_b64 vcc, vcc, s[2:3]
	s_mov_b64 s[2:3], vcc
	s_cmp_eq_u64 s[2:3], exec
	s_cbranch_scc1 .LBB0_859
	v_mov_b32_e32 v182, v179
	ds_read_b128 v[184:187], v181 offset:4608
	ds_read_b128 v[188:191], v181 offset:4640
	v_cvt_f32_i32_e32 v112, v182
	v_cmp_gt_i32_e64 s[2:3], s11, v150
	v_cmp_lt_i32_e64 s[4:5], s4, v178
	s_or_b64 s[2:3], s[2:3], s[4:5]
	v_mul_f32_e64 v112, -v152, v112
	v_cndmask_b32_e32 v126, v112, v164, vcc
	v_sub_f32_e32 v126, v126, v249
	v_fma_f32 v112, 0, v152, v126
	v_add_f32_e32 v113, v152, v126
	v_pk_fma_f32 v[114:115], v[152:153], s[72:73], v[126:127] op_sel_hi:[1,1,0]
	v_pk_fma_f32 v[116:117], v[152:153], s[74:75], v[126:127] op_sel_hi:[1,1,0]
	v_pk_fma_f32 v[118:119], v[152:153], s[76:77], v[126:127] op_sel_hi:[1,1,0]
	v_pk_fma_f32 v[120:121], v[152:153], s[70:71], v[126:127] op_sel_hi:[1,1,0]
	v_pk_fma_f32 v[122:123], v[152:153], s[78:79], v[126:127] op_sel_hi:[1,1,0]
	v_pk_fma_f32 v[124:125], v[152:153], s[80:81], v[126:127] op_sel_hi:[1,1,0]
	v_pk_fma_f32 v[126:127], v[152:153], s[82:83], v[126:127] op_sel_hi:[1,1,0]
	s_xor_b64 s[4:5], vcc, -1
	s_and_b64 s[2:3], s[2:3], s[4:5]
	s_waitcnt lgkmcnt(1)
	v_mfma_f32_32x32x16_bf16 v[112:127], v[184:187], v[128:131], v[112:127]
	s_waitcnt lgkmcnt(0)
	v_mfma_f32_32x32x16_bf16 v[112:127], v[188:191], v[132:135], v[112:127]
	ds_read_b128 v[184:187], v181 offset:4672
	ds_read_b128 v[188:191], v181 offset:4704
	s_waitcnt lgkmcnt(1)
	v_mfma_f32_32x32x16_bf16 v[112:127], v[184:187], v[136:139], v[112:127]
	s_waitcnt lgkmcnt(0)
	v_mfma_f32_32x32x16_bf16 v[112:127], v[188:191], v[140:143], v[112:127]
	s_cmp_lg_u64 s[2:3], 0
	s_cbranch_scc0 .LBB0_856
	v_cmp_gt_u32_e32 vcc, s89, v182
	v_add_u32_e32 v181, -1, v182
	s_nop 8
	v_cndmask_b32_e32 v112, v164, v112, vcc
	v_cmp_gt_u32_e32 vcc, s89, v181
	v_add_u32_e32 v181, -2, v182
	s_nop 0
	v_cndmask_b32_e32 v113, v164, v113, vcc
	v_cmp_gt_u32_e32 vcc, s89, v181
	v_add_u32_e32 v181, -3, v182
	s_nop 0
	v_cndmask_b32_e32 v114, v164, v114, vcc
	v_cmp_gt_u32_e32 vcc, s89, v181
	v_add_u32_e32 v181, -8, v182
	s_nop 0
	v_cndmask_b32_e32 v115, v164, v115, vcc
	v_cmp_gt_u32_e32 vcc, s89, v181
	v_add_u32_e32 v181, -9, v182
	s_nop 0
	v_cndmask_b32_e32 v116, v164, v116, vcc
	v_cmp_gt_u32_e32 vcc, s89, v181
	v_add_u32_e32 v181, -10, v182
	s_nop 0
	v_cndmask_b32_e32 v117, v164, v117, vcc
	v_cmp_gt_u32_e32 vcc, s89, v181
	v_add_u32_e32 v181, -11, v182
	s_nop 0
	v_cndmask_b32_e32 v118, v164, v118, vcc
	v_cmp_gt_u32_e32 vcc, s89, v181
	v_add_u32_e32 v181, -16, v182
	s_nop 0
	v_cndmask_b32_e32 v119, v164, v119, vcc
	v_cmp_gt_u32_e32 vcc, s89, v181
	v_subrev_u32_e32 v181, 17, v182
	s_nop 0
	v_cndmask_b32_e32 v120, v164, v120, vcc
	v_cmp_gt_u32_e32 vcc, s89, v181
	v_subrev_u32_e32 v181, 18, v182
	s_nop 0
	v_cndmask_b32_e32 v121, v164, v121, vcc
	v_cmp_gt_u32_e32 vcc, s89, v181
	v_subrev_u32_e32 v181, 19, v182
	s_nop 0
	v_cndmask_b32_e32 v122, v164, v122, vcc
	v_cmp_gt_u32_e32 vcc, s89, v181
	v_subrev_u32_e32 v181, 24, v182
	s_nop 0
	v_cndmask_b32_e32 v123, v164, v123, vcc
	v_cmp_gt_u32_e32 vcc, s89, v181
	v_subrev_u32_e32 v181, 25, v182
	s_nop 0
	v_cndmask_b32_e32 v124, v164, v124, vcc
	v_cmp_gt_u32_e32 vcc, s89, v181
	v_subrev_u32_e32 v181, 26, v182
	s_nop 0
	v_cndmask_b32_e32 v125, v164, v125, vcc
	v_cmp_gt_u32_e32 vcc, s89, v181
	v_subrev_u32_e32 v181, 27, v182
	s_nop 0
	v_cndmask_b32_e32 v126, v164, v126, vcc
	v_cmp_gt_u32_e32 vcc, s89, v181
	s_nop 1
	v_cndmask_b32_e32 v127, v164, v127, vcc
